# hand-written gated-DeltaNet recurrence item: packed f32, per-chunk decay normalisation, DPP row_newbcast scalars (on top of RWKV rewrite)
# speedup vs baseline: 1.1496x; 1.0747x over previous
; __device__ __forceinline__ int otid() { int t = threadIdx.x; asm volatile("" : "+v"(t)); return t; }
; __device__ __forceinline__ void gdn_item(const Params& p, int item, float* sm) {
;     ...
;   const int tid = otid(), lane = tid & 63, wave = tid >> 6;
;   const int sub = lane & 15, cw = wave * 4 + (lane >> 4);
;   const int ltt = tid >> 4, lseg = tid & 15;
;   float S[8];
; #pragma unroll
;   for (int i = 0; i < 8; i++) S[i] = 0.f;
;   const size_t rowb = (size_t)b * LP;
;   uint4 pq, pk; bf16_t pv; float pg = 0.f, pb = 0.f;
;     ...
;   __syncthreads();
;   GDN_LOAD(PADR)
;   GDN_STORE(0)
;   __syncthreads();
;   constexpr int NCH = (LP - PADR) / TC;
;   for (int ch = 0; ch < NCH; ch++) {
;     const int bi = ch & 1;
;     const int t0 = PADR + ch * TC;
;     if (ch + 1 < NCH) GDN_LOAD(t0 + TC)
.Lgd_item:
	v_readlane_b32 s14, v244, 27
	v_readlane_b32 s8, v247, 3
	v_readlane_b32 s9, v247, 4
	v_readlane_b32 s4, v247, 1
	v_readlane_b32 s5, v247, 2
	v_and_b32_e32 v136, 15, v2
	v_lshrrev_b32_e32 v137, 4, v2
	s_lshr_b32 s10, s14, 5
	s_bfe_u32 s11, s14, 0x20003
	s_and_b32 s12, s14, 7
	s_lshl_b32 s12, s12, 5
	s_mul_i32 s13, s10, 0x2080
	s_add_i32 s13, s13, 0x70
	s_add_u32 s6, s8, 0x19c8c000
	s_addc_u32 s7, s9, 0
	s_add_u32 s8, s8, 0x19d90000
	s_addc_u32 s9, s9, 0
	v_lshlrev_b32_e32 v45, 4, v136
	v_lshlrev_b32_e32 v132, 6, v137
	v_add_u32_e32 v132, 16384, v132
	v_lshlrev_b32_e32 v128, 5, v2
	v_lshl_add_u32 v129, v136, 4, v137
	v_lshlrev_b32_e32 v129, 2, v129
	v_add_u32_e32 v129, 16384, v129
	v_lshlrev_b32_e32 v130, 2, v137
	v_add_u32_e32 v130, 17472, v130
	v_lshlrev_b32_e32 v131, 2, v2
	v_add_u32_e32 v131, 17472, v131
	v_lshlrev_b32_e32 v133, 2, v137
	v_add_u32_e32 v133, 17408, v133
	v_lshlrev_b32_e32 v134, 2, v136
	v_add_u32_e32 v134, 17408, v134
	v_add_u32_e32 v138, s13, v137
	s_lshl_b32 s14, s11, 8
	v_lshl_add_u32 v139, v136, 4, s14
	s_movk_i32 s15, 0xc00
	v_mad_u32_u24 v24, v138, s15, v139
	s_add_i32 s14, s14, s12
	v_lshl_add_u32 v140, v136, 1, s14
	v_mad_u32_u24 v25, v138, s15, v140
	v_add_u32_e32 v25, 0x800, v25
	v_lshl_add_u32 v27, v138, 11, v140
	v_add_u32_e32 v27, 0x400, v27
	v_add_u32_e32 v141, s13, v136
	s_lshl_b32 s14, s11, 2
	v_lshl_add_u32 v26, v141, 5, s14
	v_mov_b32_e32 v12, 0
	v_mov_b32_e32 v13, 0
	v_mov_b32_e32 v14, 0
	v_mov_b32_e32 v15, 0
	v_mov_b32_e32 v16, 0
	v_mov_b32_e32 v17, 0
	v_mov_b32_e32 v18, 0
	v_mov_b32_e32 v19, 0
	s_barrier
	global_load_dwordx4 v[28:31], v24, s[4:5]
	global_load_dwordx4 v[32:35], v24, s[4:5] offset:1024
	global_load_ushort v36, v25, s[4:5]
	global_load_dword v37, v26, s[6:7]
	global_load_dword v38, v26, s[6:7] offset:16
	v_mov_b32_e32 v39, v128
	v_mov_b32_e32 v40, v129
	v_mov_b32_e32 v43, v133
	s_waitcnt vmcnt(0)
	v_lshlrev_b32_e32 v48, 16, v28
	v_and_b32_e32 v49, 0xffff0000, v28
	v_lshlrev_b32_e32 v50, 16, v29
	v_and_b32_e32 v51, 0xffff0000, v29
	v_lshlrev_b32_e32 v52, 16, v30
	v_and_b32_e32 v53, 0xffff0000, v30
	v_lshlrev_b32_e32 v54, 16, v31
	v_and_b32_e32 v55, 0xffff0000, v31
	v_lshlrev_b32_e32 v56, 16, v32
	v_and_b32_e32 v57, 0xffff0000, v32
	v_lshlrev_b32_e32 v58, 16, v33
	v_and_b32_e32 v59, 0xffff0000, v33
	v_lshlrev_b32_e32 v60, 16, v34
	v_and_b32_e32 v61, 0xffff0000, v34
	v_lshlrev_b32_e32 v62, 16, v35
	v_and_b32_e32 v63, 0xffff0000, v35
	v_lshlrev_b32_e32 v64, 16, v36
	v_mov_b32_e32 v65, v37
	ds_write_b128 v39, v[48:51]
	ds_write_b128 v39, v[52:55] offset:16
	v_add_f32_dpp v65, v65, v65 row_shr:1 row_mask:0xf bank_mask:0xf bound_ctrl:1
	ds_write_b128 v39, v[56:59] offset:8192
	ds_write_b128 v39, v[60:63] offset:8208
	v_add_f32_dpp v65, v65, v65 row_shr:2 row_mask:0xf bank_mask:0xf bound_ctrl:1
	v_pk_mul_f32 v[66:67], v[48:49], v[56:57]
	v_pk_fma_f32 v[66:67], v[50:51], v[58:59], v[66:67]
	v_add_f32_dpp v65, v65, v65 row_shr:4 row_mask:0xf bank_mask:0xf bound_ctrl:1
	v_pk_fma_f32 v[66:67], v[52:53], v[60:61], v[66:67]
	v_pk_fma_f32 v[66:67], v[54:55], v[62:63], v[66:67]
	v_add_f32_dpp v65, v65, v65 row_shr:8 row_mask:0xf bank_mask:0xf bound_ctrl:1
	v_add_f32_e32 v68, v66, v67
	ds_write_b32 v40, v64
	v_max_f32_e32 v65, 0xc2a00000, v65
	v_add_f32_dpp v68, v68, v68 quad_perm:[1,0,3,2] row_mask:0xf bank_mask:0xf bound_ctrl:1
	v_mul_f32_e32 v65, 0x3fb8aa3b, v65
	s_nop 0
	v_add_f32_dpp v68, v68, v68 quad_perm:[2,3,0,1] row_mask:0xf bank_mask:0xf bound_ctrl:1
	v_exp_f32_e32 v69, v65
	v_exp_f32_e64 v70, -v65
	v_add_f32_dpp v68, v68, v68 row_half_mirror row_mask:0xf bank_mask:0xf bound_ctrl:1
	s_nop 1
	v_add_f32_dpp v68, v68, v68 row_mirror row_mask:0xf bank_mask:0xf bound_ctrl:1
	v_mul_f32_e32 v23, 0x3db504f3, v69
	v_mul_f32_e32 v21, v38, v70
	v_sub_f32_e32 v20, 0, v69
	ds_write_b32 v43, v68
	s_add_u32 s4, s4, 0xc000
	s_addc_u32 s5, s5, 0
	s_add_u32 s6, s6, 0x200
	s_addc_u32 s7, s7, 0
	s_mov_b32 s0, 0
	s_mov_b32 s1, 0
	v_mov_b32_e32 v10, v45
	v_mov_b32_e32 v11, v132
	v_mov_b32_e32 v44, v134
	s_waitcnt lgkmcnt(0)
	s_barrier
	ds_read_b32 v22, v44
	ds_read_b128 v[88:91], v11 offset:0
	ds_read_b128 v[92:95], v11 offset:16
	ds_read_b128 v[96:99], v11 offset:32
	ds_read_b128 v[100:103], v11 offset:48
	ds_read_b128 v[48:51], v10 offset:8192
	ds_read_b128 v[52:55], v10 offset:8448
	ds_read_b128 v[56:59], v10
	ds_read_b128 v[60:63], v10 offset:256
	s_waitcnt lgkmcnt(8)
	v_mul_f32_e32 v22, 0x3d800000, v22
.Lgd_chunk:
	s_cmp_eq_u32 s0, 512
	s_cbranch_scc1 .Lgd_noload
	global_load_dwordx4 v[28:31], v24, s[4:5]
	global_load_dwordx4 v[32:35], v24, s[4:5] offset:1024
	global_load_ushort v36, v25, s[4:5]
	global_load_dword v37, v26, s[6:7]
	global_load_dword v38, v26, s[6:7] offset:16
; __device__ __forceinline__ void gdn_item(const Params& p, int item, float* sm) {
;     ...
;       for (int t = 0; t < TC; t++) {
;         const float4 k0 = *(const float4*)(bk + t * 128 + sub * 4);
;         const float4 k1 = *(const float4*)(bk + t * 128 + 64 + sub * 4);
;         const float4 q0 = *(const float4*)(bq + t * 128 + sub * 4);
;         const float4 q1 = *(const float4*)(bq + t * 128 + 64 + sub * 4);
;         const float v = bv[t * 16 + cw];
;         const float g = bg[t], be = bg[TC + t];
;         const float qk = bo[TC * 16 + t];
;         float pa = k0.x * S[0] + k0.y * S[1];
;         float pb2 = k0.z * S[2] + k0.w * S[3];
;         float qa = q0.x * S[0] + q0.y * S[1];
;         float qb2 = q0.z * S[2] + q0.w * S[3];
;         pa += k1.x * S[4] + k1.y * S[5];
;         pb2 += k1.z * S[6] + k1.w * S[7];
;         qa += q1.x * S[4] + q1.y * S[5];
;         qb2 += q1.z * S[6] + q1.w * S[7];
;         const float ks = dpp_sum16(pa + pb2);
;         const float qs = dpp_sum16(qa + qb2);
;         const float coef = be * (v - g * ks);
;         const float oo = g * qs + coef * qk;
;         S[0] = g * S[0] + coef * k0.x; S[1] = g * S[1] + coef * k0.y; S[2] = g * S[2] + coef * k0.z; S[3] = g * S[3] + coef * k0.w;
;         S[4] = g * S[4] + coef * k1.x; S[5] = g * S[5] + coef * k1.y; S[6] = g * S[6] + coef * k1.z; S[7] = g * S[7] + coef * k1.w;
;         oreg[t] = oo * 0.08838834764831845f;
;       }
.Lgd_noload:
	s_waitcnt lgkmcnt(0)
	v_pk_mul_f32 v[120:121], v[12:13], v[48:49]
	v_pk_fma_f32 v[120:121], v[14:15], v[50:51], v[120:121]
	v_pk_fma_f32 v[120:121], v[16:17], v[52:53], v[120:121]
	v_pk_fma_f32 v[120:121], v[18:19], v[54:55], v[120:121]
	v_pk_mul_f32 v[122:123], v[12:13], v[56:57]
	v_add_f32_e32 v124, v120, v121
	v_pk_fma_f32 v[122:123], v[14:15], v[58:59], v[122:123]
	v_pk_fma_f32 v[122:123], v[16:17], v[60:61], v[122:123]
	v_add_f32_dpp v124, v124, v124 quad_perm:[1,0,3,2] row_mask:0xf bank_mask:0xf bound_ctrl:1
	v_pk_fma_f32 v[122:123], v[18:19], v[62:63], v[122:123]
	ds_read_b128 v[64:67], v10 offset:8704
	v_add_f32_dpp v124, v124, v124 quad_perm:[2,3,0,1] row_mask:0xf bank_mask:0xf bound_ctrl:1
	v_add_f32_e32 v104, v122, v123
	ds_read_b128 v[68:71], v10 offset:8960
	v_add_f32_dpp v124, v124, v124 row_half_mirror row_mask:0xf bank_mask:0xf bound_ctrl:1
	ds_read_b128 v[72:75], v10 offset:512
	ds_read_b128 v[76:79], v10 offset:768
	v_add_f32_dpp v124, v124, v124 row_mirror row_mask:0xf bank_mask:0xf bound_ctrl:1
	v_fmac_f32_dpp v88, v20, v124 row_newbcast:0 row_mask:0xf bank_mask:0xf
	v_mul_f32_dpp v126, v21, v88 row_newbcast:0 row_mask:0xf bank_mask:0xf
	v_pk_fma_f32 v[12:13], v[48:49], v[126:127], v[12:13] op_sel_hi:[1,0,1]
	v_pk_fma_f32 v[14:15], v[50:51], v[126:127], v[14:15] op_sel_hi:[1,0,1]
	v_pk_fma_f32 v[16:17], v[52:53], v[126:127], v[16:17] op_sel_hi:[1,0,1]
	v_pk_fma_f32 v[18:19], v[54:55], v[126:127], v[18:19] op_sel_hi:[1,0,1]
	v_fmac_f32_dpp v104, v22, v126 row_newbcast:0 row_mask:0xf bank_mask:0xf
	s_waitcnt lgkmcnt(0)
	v_pk_mul_f32 v[120:121], v[12:13], v[64:65]
	v_pk_fma_f32 v[120:121], v[14:15], v[66:67], v[120:121]
	v_pk_fma_f32 v[120:121], v[16:17], v[68:69], v[120:121]
	v_pk_fma_f32 v[120:121], v[18:19], v[70:71], v[120:121]
	v_pk_mul_f32 v[122:123], v[12:13], v[72:73]
	v_add_f32_e32 v124, v120, v121
	v_pk_fma_f32 v[122:123], v[14:15], v[74:75], v[122:123]
	v_pk_fma_f32 v[122:123], v[16:17], v[76:77], v[122:123]
	v_add_f32_dpp v124, v124, v124 quad_perm:[1,0,3,2] row_mask:0xf bank_mask:0xf bound_ctrl:1
	v_pk_fma_f32 v[122:123], v[18:19], v[78:79], v[122:123]
	ds_read_b128 v[48:51], v10 offset:9216
	v_add_f32_dpp v124, v124, v124 quad_perm:[2,3,0,1] row_mask:0xf bank_mask:0xf bound_ctrl:1
	v_add_f32_e32 v105, v122, v123
	ds_read_b128 v[52:55], v10 offset:9472
	v_add_f32_dpp v124, v124, v124 row_half_mirror row_mask:0xf bank_mask:0xf bound_ctrl:1
	ds_read_b128 v[56:59], v10 offset:1024
	ds_read_b128 v[60:63], v10 offset:1280
	v_add_f32_dpp v124, v124, v124 row_mirror row_mask:0xf bank_mask:0xf bound_ctrl:1
	v_fmac_f32_dpp v89, v20, v124 row_newbcast:1 row_mask:0xf bank_mask:0xf
	v_mul_f32_dpp v126, v21, v89 row_newbcast:1 row_mask:0xf bank_mask:0xf
	v_pk_fma_f32 v[12:13], v[64:65], v[126:127], v[12:13] op_sel_hi:[1,0,1]
	v_pk_fma_f32 v[14:15], v[66:67], v[126:127], v[14:15] op_sel_hi:[1,0,1]
	v_pk_fma_f32 v[16:17], v[68:69], v[126:127], v[16:17] op_sel_hi:[1,0,1]
	v_pk_fma_f32 v[18:19], v[70:71], v[126:127], v[18:19] op_sel_hi:[1,0,1]
	v_fmac_f32_dpp v105, v22, v126 row_newbcast:1 row_mask:0xf bank_mask:0xf
	s_waitcnt lgkmcnt(0)
	v_pk_mul_f32 v[120:121], v[12:13], v[48:49]
	v_pk_fma_f32 v[120:121], v[14:15], v[50:51], v[120:121]
	v_pk_fma_f32 v[120:121], v[16:17], v[52:53], v[120:121]
	v_pk_fma_f32 v[120:121], v[18:19], v[54:55], v[120:121]
	v_pk_mul_f32 v[122:123], v[12:13], v[56:57]
	v_add_f32_e32 v124, v120, v121
	v_pk_fma_f32 v[122:123], v[14:15], v[58:59], v[122:123]
	v_pk_fma_f32 v[122:123], v[16:17], v[60:61], v[122:123]
	v_add_f32_dpp v124, v124, v124 quad_perm:[1,0,3,2] row_mask:0xf bank_mask:0xf bound_ctrl:1
	v_pk_fma_f32 v[122:123], v[18:19], v[62:63], v[122:123]
	ds_read_b128 v[64:67], v10 offset:9728
	v_add_f32_dpp v124, v124, v124 quad_perm:[2,3,0,1] row_mask:0xf bank_mask:0xf bound_ctrl:1
	v_add_f32_e32 v106, v122, v123
	ds_read_b128 v[68:71], v10 offset:9984
	v_add_f32_dpp v124, v124, v124 row_half_mirror row_mask:0xf bank_mask:0xf bound_ctrl:1
	ds_read_b128 v[72:75], v10 offset:1536
	ds_read_b128 v[76:79], v10 offset:1792
	v_add_f32_dpp v124, v124, v124 row_mirror row_mask:0xf bank_mask:0xf bound_ctrl:1
	v_fmac_f32_dpp v90, v20, v124 row_newbcast:2 row_mask:0xf bank_mask:0xf
	v_mul_f32_dpp v126, v21, v90 row_newbcast:2 row_mask:0xf bank_mask:0xf
	v_pk_fma_f32 v[12:13], v[48:49], v[126:127], v[12:13] op_sel_hi:[1,0,1]
	v_pk_fma_f32 v[14:15], v[50:51], v[126:127], v[14:15] op_sel_hi:[1,0,1]
	v_pk_fma_f32 v[16:17], v[52:53], v[126:127], v[16:17] op_sel_hi:[1,0,1]
	v_pk_fma_f32 v[18:19], v[54:55], v[126:127], v[18:19] op_sel_hi:[1,0,1]
	v_fmac_f32_dpp v106, v22, v126 row_newbcast:2 row_mask:0xf bank_mask:0xf
	s_waitcnt lgkmcnt(0)
	v_pk_mul_f32 v[120:121], v[12:13], v[64:65]
	v_pk_fma_f32 v[120:121], v[14:15], v[66:67], v[120:121]
	v_pk_fma_f32 v[120:121], v[16:17], v[68:69], v[120:121]
	v_pk_fma_f32 v[120:121], v[18:19], v[70:71], v[120:121]
	v_pk_mul_f32 v[122:123], v[12:13], v[72:73]
	v_add_f32_e32 v124, v120, v121
	v_pk_fma_f32 v[122:123], v[14:15], v[74:75], v[122:123]
	v_pk_fma_f32 v[122:123], v[16:17], v[76:77], v[122:123]
	v_add_f32_dpp v124, v124, v124 quad_perm:[1,0,3,2] row_mask:0xf bank_mask:0xf bound_ctrl:1
	v_pk_fma_f32 v[122:123], v[18:19], v[78:79], v[122:123]
	ds_read_b128 v[48:51], v10 offset:10240
	v_add_f32_dpp v124, v124, v124 quad_perm:[2,3,0,1] row_mask:0xf bank_mask:0xf bound_ctrl:1
	v_add_f32_e32 v107, v122, v123
	ds_read_b128 v[52:55], v10 offset:10496
	v_add_f32_dpp v124, v124, v124 row_half_mirror row_mask:0xf bank_mask:0xf bound_ctrl:1
	ds_read_b128 v[56:59], v10 offset:2048
	ds_read_b128 v[60:63], v10 offset:2304
	v_add_f32_dpp v124, v124, v124 row_mirror row_mask:0xf bank_mask:0xf bound_ctrl:1
	v_fmac_f32_dpp v91, v20, v124 row_newbcast:3 row_mask:0xf bank_mask:0xf
	v_mul_f32_dpp v126, v21, v91 row_newbcast:3 row_mask:0xf bank_mask:0xf
	v_pk_fma_f32 v[12:13], v[64:65], v[126:127], v[12:13] op_sel_hi:[1,0,1]
	v_pk_fma_f32 v[14:15], v[66:67], v[126:127], v[14:15] op_sel_hi:[1,0,1]
	v_pk_fma_f32 v[16:17], v[68:69], v[126:127], v[16:17] op_sel_hi:[1,0,1]
	v_pk_fma_f32 v[18:19], v[70:71], v[126:127], v[18:19] op_sel_hi:[1,0,1]
	v_fmac_f32_dpp v107, v22, v126 row_newbcast:3 row_mask:0xf bank_mask:0xf
	s_waitcnt lgkmcnt(0)
; __device__ __forceinline__ void gdn_item(const Params& p, int item, float* sm) {
;     ...
;       for (int t = 0; t < TC; t++) {
;         const float4 k0 = *(const float4*)(bk + t * 128 + sub * 4);
;         const float4 k1 = *(const float4*)(bk + t * 128 + 64 + sub * 4);
;         const float4 q0 = *(const float4*)(bq + t * 128 + sub * 4);
;         const float4 q1 = *(const float4*)(bq + t * 128 + 64 + sub * 4);
;         const float v = bv[t * 16 + cw];
;         const float g = bg[t], be = bg[TC + t];
;         const float qk = bo[TC * 16 + t];
;         float pa = k0.x * S[0] + k0.y * S[1];
;         float pb2 = k0.z * S[2] + k0.w * S[3];
;         float qa = q0.x * S[0] + q0.y * S[1];
;         float qb2 = q0.z * S[2] + q0.w * S[3];
;         pa += k1.x * S[4] + k1.y * S[5];
;         pb2 += k1.z * S[6] + k1.w * S[7];
;         qa += q1.x * S[4] + q1.y * S[5];
;         qb2 += q1.z * S[6] + q1.w * S[7];
;         const float ks = dpp_sum16(pa + pb2);
;         const float qs = dpp_sum16(qa + qb2);
;         const float coef = be * (v - g * ks);
;         const float oo = g * qs + coef * qk;
;         S[0] = g * S[0] + coef * k0.x; S[1] = g * S[1] + coef * k0.y; S[2] = g * S[2] + coef * k0.z; S[3] = g * S[3] + coef * k0.w;
;         S[4] = g * S[4] + coef * k1.x; S[5] = g * S[5] + coef * k1.y; S[6] = g * S[6] + coef * k1.z; S[7] = g * S[7] + coef * k1.w;
;         oreg[t] = oo * 0.08838834764831845f;
;       }
	v_pk_mul_f32 v[120:121], v[12:13], v[48:49]
	v_pk_fma_f32 v[120:121], v[14:15], v[50:51], v[120:121]
	v_pk_fma_f32 v[120:121], v[16:17], v[52:53], v[120:121]
	v_pk_fma_f32 v[120:121], v[18:19], v[54:55], v[120:121]
	v_pk_mul_f32 v[122:123], v[12:13], v[56:57]
	v_add_f32_e32 v124, v120, v121
	v_pk_fma_f32 v[122:123], v[14:15], v[58:59], v[122:123]
	v_pk_fma_f32 v[122:123], v[16:17], v[60:61], v[122:123]
	v_add_f32_dpp v124, v124, v124 quad_perm:[1,0,3,2] row_mask:0xf bank_mask:0xf bound_ctrl:1
	v_pk_fma_f32 v[122:123], v[18:19], v[62:63], v[122:123]
	ds_read_b128 v[64:67], v10 offset:10752
	v_add_f32_dpp v124, v124, v124 quad_perm:[2,3,0,1] row_mask:0xf bank_mask:0xf bound_ctrl:1
	v_add_f32_e32 v108, v122, v123
	ds_read_b128 v[68:71], v10 offset:11008
	v_add_f32_dpp v124, v124, v124 row_half_mirror row_mask:0xf bank_mask:0xf bound_ctrl:1
	ds_read_b128 v[72:75], v10 offset:2560
	ds_read_b128 v[76:79], v10 offset:2816
	v_add_f32_dpp v124, v124, v124 row_mirror row_mask:0xf bank_mask:0xf bound_ctrl:1
	v_fmac_f32_dpp v92, v20, v124 row_newbcast:4 row_mask:0xf bank_mask:0xf
	v_mul_f32_dpp v126, v21, v92 row_newbcast:4 row_mask:0xf bank_mask:0xf
	v_pk_fma_f32 v[12:13], v[48:49], v[126:127], v[12:13] op_sel_hi:[1,0,1]
	v_pk_fma_f32 v[14:15], v[50:51], v[126:127], v[14:15] op_sel_hi:[1,0,1]
	v_pk_fma_f32 v[16:17], v[52:53], v[126:127], v[16:17] op_sel_hi:[1,0,1]
	v_pk_fma_f32 v[18:19], v[54:55], v[126:127], v[18:19] op_sel_hi:[1,0,1]
	v_fmac_f32_dpp v108, v22, v126 row_newbcast:4 row_mask:0xf bank_mask:0xf
	s_waitcnt lgkmcnt(0)
	v_pk_mul_f32 v[120:121], v[12:13], v[64:65]
	v_pk_fma_f32 v[120:121], v[14:15], v[66:67], v[120:121]
	v_pk_fma_f32 v[120:121], v[16:17], v[68:69], v[120:121]
	v_pk_fma_f32 v[120:121], v[18:19], v[70:71], v[120:121]
	v_pk_mul_f32 v[122:123], v[12:13], v[72:73]
	v_add_f32_e32 v124, v120, v121
	v_pk_fma_f32 v[122:123], v[14:15], v[74:75], v[122:123]
	v_pk_fma_f32 v[122:123], v[16:17], v[76:77], v[122:123]
	v_add_f32_dpp v124, v124, v124 quad_perm:[1,0,3,2] row_mask:0xf bank_mask:0xf bound_ctrl:1
	v_pk_fma_f32 v[122:123], v[18:19], v[78:79], v[122:123]
	ds_read_b128 v[48:51], v10 offset:11264
	v_add_f32_dpp v124, v124, v124 quad_perm:[2,3,0,1] row_mask:0xf bank_mask:0xf bound_ctrl:1
	v_add_f32_e32 v109, v122, v123
	ds_read_b128 v[52:55], v10 offset:11520
	v_add_f32_dpp v124, v124, v124 row_half_mirror row_mask:0xf bank_mask:0xf bound_ctrl:1
	ds_read_b128 v[56:59], v10 offset:3072
	ds_read_b128 v[60:63], v10 offset:3328
	v_add_f32_dpp v124, v124, v124 row_mirror row_mask:0xf bank_mask:0xf bound_ctrl:1
	v_fmac_f32_dpp v93, v20, v124 row_newbcast:5 row_mask:0xf bank_mask:0xf
	v_mul_f32_dpp v126, v21, v93 row_newbcast:5 row_mask:0xf bank_mask:0xf
	v_pk_fma_f32 v[12:13], v[64:65], v[126:127], v[12:13] op_sel_hi:[1,0,1]
	v_pk_fma_f32 v[14:15], v[66:67], v[126:127], v[14:15] op_sel_hi:[1,0,1]
	v_pk_fma_f32 v[16:17], v[68:69], v[126:127], v[16:17] op_sel_hi:[1,0,1]
	v_pk_fma_f32 v[18:19], v[70:71], v[126:127], v[18:19] op_sel_hi:[1,0,1]
	v_fmac_f32_dpp v109, v22, v126 row_newbcast:5 row_mask:0xf bank_mask:0xf
	s_waitcnt lgkmcnt(0)
	v_pk_mul_f32 v[120:121], v[12:13], v[48:49]
	v_pk_fma_f32 v[120:121], v[14:15], v[50:51], v[120:121]
	v_pk_fma_f32 v[120:121], v[16:17], v[52:53], v[120:121]
	v_pk_fma_f32 v[120:121], v[18:19], v[54:55], v[120:121]
	v_pk_mul_f32 v[122:123], v[12:13], v[56:57]
	v_add_f32_e32 v124, v120, v121
	v_pk_fma_f32 v[122:123], v[14:15], v[58:59], v[122:123]
	v_pk_fma_f32 v[122:123], v[16:17], v[60:61], v[122:123]
	v_add_f32_dpp v124, v124, v124 quad_perm:[1,0,3,2] row_mask:0xf bank_mask:0xf bound_ctrl:1
	v_pk_fma_f32 v[122:123], v[18:19], v[62:63], v[122:123]
	ds_read_b128 v[64:67], v10 offset:11776
	v_add_f32_dpp v124, v124, v124 quad_perm:[2,3,0,1] row_mask:0xf bank_mask:0xf bound_ctrl:1
	v_add_f32_e32 v110, v122, v123
	ds_read_b128 v[68:71], v10 offset:12032
	v_add_f32_dpp v124, v124, v124 row_half_mirror row_mask:0xf bank_mask:0xf bound_ctrl:1
	ds_read_b128 v[72:75], v10 offset:3584
	ds_read_b128 v[76:79], v10 offset:3840
	v_add_f32_dpp v124, v124, v124 row_mirror row_mask:0xf bank_mask:0xf bound_ctrl:1
	v_fmac_f32_dpp v94, v20, v124 row_newbcast:6 row_mask:0xf bank_mask:0xf
	v_mul_f32_dpp v126, v21, v94 row_newbcast:6 row_mask:0xf bank_mask:0xf
	v_pk_fma_f32 v[12:13], v[48:49], v[126:127], v[12:13] op_sel_hi:[1,0,1]
	v_pk_fma_f32 v[14:15], v[50:51], v[126:127], v[14:15] op_sel_hi:[1,0,1]
	v_pk_fma_f32 v[16:17], v[52:53], v[126:127], v[16:17] op_sel_hi:[1,0,1]
	v_pk_fma_f32 v[18:19], v[54:55], v[126:127], v[18:19] op_sel_hi:[1,0,1]
	v_fmac_f32_dpp v110, v22, v126 row_newbcast:6 row_mask:0xf bank_mask:0xf
	s_waitcnt lgkmcnt(0)
	v_pk_mul_f32 v[120:121], v[12:13], v[64:65]
	v_pk_fma_f32 v[120:121], v[14:15], v[66:67], v[120:121]
	v_pk_fma_f32 v[120:121], v[16:17], v[68:69], v[120:121]
	v_pk_fma_f32 v[120:121], v[18:19], v[70:71], v[120:121]
	v_pk_mul_f32 v[122:123], v[12:13], v[72:73]
	v_add_f32_e32 v124, v120, v121
	v_pk_fma_f32 v[122:123], v[14:15], v[74:75], v[122:123]
	v_pk_fma_f32 v[122:123], v[16:17], v[76:77], v[122:123]
	v_add_f32_dpp v124, v124, v124 quad_perm:[1,0,3,2] row_mask:0xf bank_mask:0xf bound_ctrl:1
	v_pk_fma_f32 v[122:123], v[18:19], v[78:79], v[122:123]
	ds_read_b128 v[48:51], v10 offset:12288
	v_add_f32_dpp v124, v124, v124 quad_perm:[2,3,0,1] row_mask:0xf bank_mask:0xf bound_ctrl:1
	v_add_f32_e32 v111, v122, v123
	ds_read_b128 v[52:55], v10 offset:12544
	v_add_f32_dpp v124, v124, v124 row_half_mirror row_mask:0xf bank_mask:0xf bound_ctrl:1
	ds_read_b128 v[56:59], v10 offset:4096
	ds_read_b128 v[60:63], v10 offset:4352
	v_add_f32_dpp v124, v124, v124 row_mirror row_mask:0xf bank_mask:0xf bound_ctrl:1
	v_fmac_f32_dpp v95, v20, v124 row_newbcast:7 row_mask:0xf bank_mask:0xf
	v_mul_f32_dpp v126, v21, v95 row_newbcast:7 row_mask:0xf bank_mask:0xf
	v_pk_fma_f32 v[12:13], v[64:65], v[126:127], v[12:13] op_sel_hi:[1,0,1]
	v_pk_fma_f32 v[14:15], v[66:67], v[126:127], v[14:15] op_sel_hi:[1,0,1]
	v_pk_fma_f32 v[16:17], v[68:69], v[126:127], v[16:17] op_sel_hi:[1,0,1]
	v_pk_fma_f32 v[18:19], v[70:71], v[126:127], v[18:19] op_sel_hi:[1,0,1]
	v_fmac_f32_dpp v111, v22, v126 row_newbcast:7 row_mask:0xf bank_mask:0xf
	s_waitcnt lgkmcnt(0)
; __device__ __forceinline__ void gdn_item(const Params& p, int item, float* sm) {
;     ...
;       for (int t = 0; t < TC; t++) {
;         const float4 k0 = *(const float4*)(bk + t * 128 + sub * 4);
;         const float4 k1 = *(const float4*)(bk + t * 128 + 64 + sub * 4);
;         const float4 q0 = *(const float4*)(bq + t * 128 + sub * 4);
;         const float4 q1 = *(const float4*)(bq + t * 128 + 64 + sub * 4);
;         const float v = bv[t * 16 + cw];
;         const float g = bg[t], be = bg[TC + t];
;         const float qk = bo[TC * 16 + t];
;         float pa = k0.x * S[0] + k0.y * S[1];
;         float pb2 = k0.z * S[2] + k0.w * S[3];
;         float qa = q0.x * S[0] + q0.y * S[1];
;         float qb2 = q0.z * S[2] + q0.w * S[3];
;         pa += k1.x * S[4] + k1.y * S[5];
;         pb2 += k1.z * S[6] + k1.w * S[7];
;         qa += q1.x * S[4] + q1.y * S[5];
;         qb2 += q1.z * S[6] + q1.w * S[7];
;         const float ks = dpp_sum16(pa + pb2);
;         const float qs = dpp_sum16(qa + qb2);
;         const float coef = be * (v - g * ks);
;         const float oo = g * qs + coef * qk;
;         S[0] = g * S[0] + coef * k0.x; S[1] = g * S[1] + coef * k0.y; S[2] = g * S[2] + coef * k0.z; S[3] = g * S[3] + coef * k0.w;
;         S[4] = g * S[4] + coef * k1.x; S[5] = g * S[5] + coef * k1.y; S[6] = g * S[6] + coef * k1.z; S[7] = g * S[7] + coef * k1.w;
;         oreg[t] = oo * 0.08838834764831845f;
;       }
	v_pk_mul_f32 v[120:121], v[12:13], v[48:49]
	v_pk_fma_f32 v[120:121], v[14:15], v[50:51], v[120:121]
	v_pk_fma_f32 v[120:121], v[16:17], v[52:53], v[120:121]
	v_pk_fma_f32 v[120:121], v[18:19], v[54:55], v[120:121]
	v_pk_mul_f32 v[122:123], v[12:13], v[56:57]
	v_add_f32_e32 v124, v120, v121
	v_pk_fma_f32 v[122:123], v[14:15], v[58:59], v[122:123]
	v_pk_fma_f32 v[122:123], v[16:17], v[60:61], v[122:123]
	v_add_f32_dpp v124, v124, v124 quad_perm:[1,0,3,2] row_mask:0xf bank_mask:0xf bound_ctrl:1
	v_pk_fma_f32 v[122:123], v[18:19], v[62:63], v[122:123]
	ds_read_b128 v[64:67], v10 offset:12800
	v_add_f32_dpp v124, v124, v124 quad_perm:[2,3,0,1] row_mask:0xf bank_mask:0xf bound_ctrl:1
	v_add_f32_e32 v112, v122, v123
	ds_read_b128 v[68:71], v10 offset:13056
	v_add_f32_dpp v124, v124, v124 row_half_mirror row_mask:0xf bank_mask:0xf bound_ctrl:1
	ds_read_b128 v[72:75], v10 offset:4608
	ds_read_b128 v[76:79], v10 offset:4864
	v_add_f32_dpp v124, v124, v124 row_mirror row_mask:0xf bank_mask:0xf bound_ctrl:1
	v_fmac_f32_dpp v96, v20, v124 row_newbcast:8 row_mask:0xf bank_mask:0xf
	v_mul_f32_dpp v126, v21, v96 row_newbcast:8 row_mask:0xf bank_mask:0xf
	v_pk_fma_f32 v[12:13], v[48:49], v[126:127], v[12:13] op_sel_hi:[1,0,1]
	v_pk_fma_f32 v[14:15], v[50:51], v[126:127], v[14:15] op_sel_hi:[1,0,1]
	v_pk_fma_f32 v[16:17], v[52:53], v[126:127], v[16:17] op_sel_hi:[1,0,1]
	v_pk_fma_f32 v[18:19], v[54:55], v[126:127], v[18:19] op_sel_hi:[1,0,1]
	v_fmac_f32_dpp v112, v22, v126 row_newbcast:8 row_mask:0xf bank_mask:0xf
	s_waitcnt lgkmcnt(0)
	v_pk_mul_f32 v[120:121], v[12:13], v[64:65]
	v_pk_fma_f32 v[120:121], v[14:15], v[66:67], v[120:121]
	v_pk_fma_f32 v[120:121], v[16:17], v[68:69], v[120:121]
	v_pk_fma_f32 v[120:121], v[18:19], v[70:71], v[120:121]
	v_pk_mul_f32 v[122:123], v[12:13], v[72:73]
	v_add_f32_e32 v124, v120, v121
	v_pk_fma_f32 v[122:123], v[14:15], v[74:75], v[122:123]
	v_pk_fma_f32 v[122:123], v[16:17], v[76:77], v[122:123]
	v_add_f32_dpp v124, v124, v124 quad_perm:[1,0,3,2] row_mask:0xf bank_mask:0xf bound_ctrl:1
	v_pk_fma_f32 v[122:123], v[18:19], v[78:79], v[122:123]
	ds_read_b128 v[48:51], v10 offset:13312
	v_add_f32_dpp v124, v124, v124 quad_perm:[2,3,0,1] row_mask:0xf bank_mask:0xf bound_ctrl:1
	v_add_f32_e32 v113, v122, v123
	ds_read_b128 v[52:55], v10 offset:13568
	v_add_f32_dpp v124, v124, v124 row_half_mirror row_mask:0xf bank_mask:0xf bound_ctrl:1
	ds_read_b128 v[56:59], v10 offset:5120
	ds_read_b128 v[60:63], v10 offset:5376
	v_add_f32_dpp v124, v124, v124 row_mirror row_mask:0xf bank_mask:0xf bound_ctrl:1
	v_fmac_f32_dpp v97, v20, v124 row_newbcast:9 row_mask:0xf bank_mask:0xf
	v_mul_f32_dpp v126, v21, v97 row_newbcast:9 row_mask:0xf bank_mask:0xf
	v_pk_fma_f32 v[12:13], v[64:65], v[126:127], v[12:13] op_sel_hi:[1,0,1]
	v_pk_fma_f32 v[14:15], v[66:67], v[126:127], v[14:15] op_sel_hi:[1,0,1]
	v_pk_fma_f32 v[16:17], v[68:69], v[126:127], v[16:17] op_sel_hi:[1,0,1]
	v_pk_fma_f32 v[18:19], v[70:71], v[126:127], v[18:19] op_sel_hi:[1,0,1]
	v_fmac_f32_dpp v113, v22, v126 row_newbcast:9 row_mask:0xf bank_mask:0xf
	s_waitcnt lgkmcnt(0)
	v_pk_mul_f32 v[120:121], v[12:13], v[48:49]
	v_pk_fma_f32 v[120:121], v[14:15], v[50:51], v[120:121]
	v_pk_fma_f32 v[120:121], v[16:17], v[52:53], v[120:121]
	v_pk_fma_f32 v[120:121], v[18:19], v[54:55], v[120:121]
	v_pk_mul_f32 v[122:123], v[12:13], v[56:57]
	v_add_f32_e32 v124, v120, v121
	v_pk_fma_f32 v[122:123], v[14:15], v[58:59], v[122:123]
	v_pk_fma_f32 v[122:123], v[16:17], v[60:61], v[122:123]
	v_add_f32_dpp v124, v124, v124 quad_perm:[1,0,3,2] row_mask:0xf bank_mask:0xf bound_ctrl:1
	v_pk_fma_f32 v[122:123], v[18:19], v[62:63], v[122:123]
	ds_read_b128 v[64:67], v10 offset:13824
	v_add_f32_dpp v124, v124, v124 quad_perm:[2,3,0,1] row_mask:0xf bank_mask:0xf bound_ctrl:1
	v_add_f32_e32 v114, v122, v123
	ds_read_b128 v[68:71], v10 offset:14080
	v_add_f32_dpp v124, v124, v124 row_half_mirror row_mask:0xf bank_mask:0xf bound_ctrl:1
	ds_read_b128 v[72:75], v10 offset:5632
	ds_read_b128 v[76:79], v10 offset:5888
	v_add_f32_dpp v124, v124, v124 row_mirror row_mask:0xf bank_mask:0xf bound_ctrl:1
	v_fmac_f32_dpp v98, v20, v124 row_newbcast:10 row_mask:0xf bank_mask:0xf
	v_mul_f32_dpp v126, v21, v98 row_newbcast:10 row_mask:0xf bank_mask:0xf
	v_pk_fma_f32 v[12:13], v[48:49], v[126:127], v[12:13] op_sel_hi:[1,0,1]
	v_pk_fma_f32 v[14:15], v[50:51], v[126:127], v[14:15] op_sel_hi:[1,0,1]
	v_pk_fma_f32 v[16:17], v[52:53], v[126:127], v[16:17] op_sel_hi:[1,0,1]
	v_pk_fma_f32 v[18:19], v[54:55], v[126:127], v[18:19] op_sel_hi:[1,0,1]
	v_fmac_f32_dpp v114, v22, v126 row_newbcast:10 row_mask:0xf bank_mask:0xf
	s_waitcnt lgkmcnt(0)
	v_pk_mul_f32 v[120:121], v[12:13], v[64:65]
	v_pk_fma_f32 v[120:121], v[14:15], v[66:67], v[120:121]
	v_pk_fma_f32 v[120:121], v[16:17], v[68:69], v[120:121]
	v_pk_fma_f32 v[120:121], v[18:19], v[70:71], v[120:121]
	v_pk_mul_f32 v[122:123], v[12:13], v[72:73]
	v_add_f32_e32 v124, v120, v121
	v_pk_fma_f32 v[122:123], v[14:15], v[74:75], v[122:123]
	v_pk_fma_f32 v[122:123], v[16:17], v[76:77], v[122:123]
	v_add_f32_dpp v124, v124, v124 quad_perm:[1,0,3,2] row_mask:0xf bank_mask:0xf bound_ctrl:1
	v_pk_fma_f32 v[122:123], v[18:19], v[78:79], v[122:123]
	ds_read_b128 v[48:51], v10 offset:14336
	v_add_f32_dpp v124, v124, v124 quad_perm:[2,3,0,1] row_mask:0xf bank_mask:0xf bound_ctrl:1
	v_add_f32_e32 v115, v122, v123
	ds_read_b128 v[52:55], v10 offset:14592
	v_add_f32_dpp v124, v124, v124 row_half_mirror row_mask:0xf bank_mask:0xf bound_ctrl:1
	ds_read_b128 v[56:59], v10 offset:6144
	ds_read_b128 v[60:63], v10 offset:6400
	v_add_f32_dpp v124, v124, v124 row_mirror row_mask:0xf bank_mask:0xf bound_ctrl:1
	v_fmac_f32_dpp v99, v20, v124 row_newbcast:11 row_mask:0xf bank_mask:0xf
	v_mul_f32_dpp v126, v21, v99 row_newbcast:11 row_mask:0xf bank_mask:0xf
	v_pk_fma_f32 v[12:13], v[64:65], v[126:127], v[12:13] op_sel_hi:[1,0,1]
	v_pk_fma_f32 v[14:15], v[66:67], v[126:127], v[14:15] op_sel_hi:[1,0,1]
	v_pk_fma_f32 v[16:17], v[68:69], v[126:127], v[16:17] op_sel_hi:[1,0,1]
	v_pk_fma_f32 v[18:19], v[70:71], v[126:127], v[18:19] op_sel_hi:[1,0,1]
	v_fmac_f32_dpp v115, v22, v126 row_newbcast:11 row_mask:0xf bank_mask:0xf
	s_waitcnt lgkmcnt(0)
; __device__ __forceinline__ void gdn_item(const Params& p, int item, float* sm) {
;     ...
;       for (int t = 0; t < TC; t++) {
;         const float4 k0 = *(const float4*)(bk + t * 128 + sub * 4);
;         const float4 k1 = *(const float4*)(bk + t * 128 + 64 + sub * 4);
;         const float4 q0 = *(const float4*)(bq + t * 128 + sub * 4);
;         const float4 q1 = *(const float4*)(bq + t * 128 + 64 + sub * 4);
;         const float v = bv[t * 16 + cw];
;         const float g = bg[t], be = bg[TC + t];
;         const float qk = bo[TC * 16 + t];
;         float pa = k0.x * S[0] + k0.y * S[1];
;         float pb2 = k0.z * S[2] + k0.w * S[3];
;         float qa = q0.x * S[0] + q0.y * S[1];
;         float qb2 = q0.z * S[2] + q0.w * S[3];
;         pa += k1.x * S[4] + k1.y * S[5];
;         pb2 += k1.z * S[6] + k1.w * S[7];
;         qa += q1.x * S[4] + q1.y * S[5];
;         qb2 += q1.z * S[6] + q1.w * S[7];
;         const float ks = dpp_sum16(pa + pb2);
;         const float qs = dpp_sum16(qa + qb2);
;         const float coef = be * (v - g * ks);
;         const float oo = g * qs + coef * qk;
;         S[0] = g * S[0] + coef * k0.x; S[1] = g * S[1] + coef * k0.y; S[2] = g * S[2] + coef * k0.z; S[3] = g * S[3] + coef * k0.w;
;         S[4] = g * S[4] + coef * k1.x; S[5] = g * S[5] + coef * k1.y; S[6] = g * S[6] + coef * k1.z; S[7] = g * S[7] + coef * k1.w;
;         oreg[t] = oo * 0.08838834764831845f;
;       }
	v_pk_mul_f32 v[120:121], v[12:13], v[48:49]
	v_pk_fma_f32 v[120:121], v[14:15], v[50:51], v[120:121]
	v_pk_fma_f32 v[120:121], v[16:17], v[52:53], v[120:121]
	v_pk_fma_f32 v[120:121], v[18:19], v[54:55], v[120:121]
	v_pk_mul_f32 v[122:123], v[12:13], v[56:57]
	v_add_f32_e32 v124, v120, v121
	v_pk_fma_f32 v[122:123], v[14:15], v[58:59], v[122:123]
	v_pk_fma_f32 v[122:123], v[16:17], v[60:61], v[122:123]
	v_add_f32_dpp v124, v124, v124 quad_perm:[1,0,3,2] row_mask:0xf bank_mask:0xf bound_ctrl:1
	v_pk_fma_f32 v[122:123], v[18:19], v[62:63], v[122:123]
	ds_read_b128 v[64:67], v10 offset:14848
	v_add_f32_dpp v124, v124, v124 quad_perm:[2,3,0,1] row_mask:0xf bank_mask:0xf bound_ctrl:1
	v_add_f32_e32 v116, v122, v123
	ds_read_b128 v[68:71], v10 offset:15104
	v_add_f32_dpp v124, v124, v124 row_half_mirror row_mask:0xf bank_mask:0xf bound_ctrl:1
	ds_read_b128 v[72:75], v10 offset:6656
	ds_read_b128 v[76:79], v10 offset:6912
	v_add_f32_dpp v124, v124, v124 row_mirror row_mask:0xf bank_mask:0xf bound_ctrl:1
	v_fmac_f32_dpp v100, v20, v124 row_newbcast:12 row_mask:0xf bank_mask:0xf
	v_mul_f32_dpp v126, v21, v100 row_newbcast:12 row_mask:0xf bank_mask:0xf
	v_pk_fma_f32 v[12:13], v[48:49], v[126:127], v[12:13] op_sel_hi:[1,0,1]
	v_pk_fma_f32 v[14:15], v[50:51], v[126:127], v[14:15] op_sel_hi:[1,0,1]
	v_pk_fma_f32 v[16:17], v[52:53], v[126:127], v[16:17] op_sel_hi:[1,0,1]
	v_pk_fma_f32 v[18:19], v[54:55], v[126:127], v[18:19] op_sel_hi:[1,0,1]
	v_fmac_f32_dpp v116, v22, v126 row_newbcast:12 row_mask:0xf bank_mask:0xf
	s_waitcnt lgkmcnt(0)
	v_pk_mul_f32 v[120:121], v[12:13], v[64:65]
	v_pk_fma_f32 v[120:121], v[14:15], v[66:67], v[120:121]
	v_pk_fma_f32 v[120:121], v[16:17], v[68:69], v[120:121]
	v_pk_fma_f32 v[120:121], v[18:19], v[70:71], v[120:121]
	v_pk_mul_f32 v[122:123], v[12:13], v[72:73]
	v_add_f32_e32 v124, v120, v121
	v_pk_fma_f32 v[122:123], v[14:15], v[74:75], v[122:123]
	v_pk_fma_f32 v[122:123], v[16:17], v[76:77], v[122:123]
	v_add_f32_dpp v124, v124, v124 quad_perm:[1,0,3,2] row_mask:0xf bank_mask:0xf bound_ctrl:1
	v_pk_fma_f32 v[122:123], v[18:19], v[78:79], v[122:123]
	ds_read_b128 v[48:51], v10 offset:15360
	v_add_f32_dpp v124, v124, v124 quad_perm:[2,3,0,1] row_mask:0xf bank_mask:0xf bound_ctrl:1
	v_add_f32_e32 v117, v122, v123
	ds_read_b128 v[52:55], v10 offset:15616
	v_add_f32_dpp v124, v124, v124 row_half_mirror row_mask:0xf bank_mask:0xf bound_ctrl:1
	ds_read_b128 v[56:59], v10 offset:7168
	ds_read_b128 v[60:63], v10 offset:7424
	v_add_f32_dpp v124, v124, v124 row_mirror row_mask:0xf bank_mask:0xf bound_ctrl:1
	v_fmac_f32_dpp v101, v20, v124 row_newbcast:13 row_mask:0xf bank_mask:0xf
	v_mul_f32_dpp v126, v21, v101 row_newbcast:13 row_mask:0xf bank_mask:0xf
	v_pk_fma_f32 v[12:13], v[64:65], v[126:127], v[12:13] op_sel_hi:[1,0,1]
	v_pk_fma_f32 v[14:15], v[66:67], v[126:127], v[14:15] op_sel_hi:[1,0,1]
	v_pk_fma_f32 v[16:17], v[68:69], v[126:127], v[16:17] op_sel_hi:[1,0,1]
	v_pk_fma_f32 v[18:19], v[70:71], v[126:127], v[18:19] op_sel_hi:[1,0,1]
	v_fmac_f32_dpp v117, v22, v126 row_newbcast:13 row_mask:0xf bank_mask:0xf
	s_waitcnt lgkmcnt(0)
	v_pk_mul_f32 v[120:121], v[12:13], v[48:49]
	v_pk_fma_f32 v[120:121], v[14:15], v[50:51], v[120:121]
	v_pk_fma_f32 v[120:121], v[16:17], v[52:53], v[120:121]
	v_pk_fma_f32 v[120:121], v[18:19], v[54:55], v[120:121]
	v_pk_mul_f32 v[122:123], v[12:13], v[56:57]
	v_add_f32_e32 v124, v120, v121
	v_pk_fma_f32 v[122:123], v[14:15], v[58:59], v[122:123]
	v_pk_fma_f32 v[122:123], v[16:17], v[60:61], v[122:123]
	v_add_f32_dpp v124, v124, v124 quad_perm:[1,0,3,2] row_mask:0xf bank_mask:0xf bound_ctrl:1
	v_pk_fma_f32 v[122:123], v[18:19], v[62:63], v[122:123]
	ds_read_b128 v[64:67], v10 offset:15872
	v_add_f32_dpp v124, v124, v124 quad_perm:[2,3,0,1] row_mask:0xf bank_mask:0xf bound_ctrl:1
	v_add_f32_e32 v118, v122, v123
	ds_read_b128 v[68:71], v10 offset:16128
	v_add_f32_dpp v124, v124, v124 row_half_mirror row_mask:0xf bank_mask:0xf bound_ctrl:1
	ds_read_b128 v[72:75], v10 offset:7680
	ds_read_b128 v[76:79], v10 offset:7936
	v_add_f32_dpp v124, v124, v124 row_mirror row_mask:0xf bank_mask:0xf bound_ctrl:1
	v_fmac_f32_dpp v102, v20, v124 row_newbcast:14 row_mask:0xf bank_mask:0xf
	v_mul_f32_dpp v126, v21, v102 row_newbcast:14 row_mask:0xf bank_mask:0xf
	v_pk_fma_f32 v[12:13], v[48:49], v[126:127], v[12:13] op_sel_hi:[1,0,1]
	v_pk_fma_f32 v[14:15], v[50:51], v[126:127], v[14:15] op_sel_hi:[1,0,1]
	v_pk_fma_f32 v[16:17], v[52:53], v[126:127], v[16:17] op_sel_hi:[1,0,1]
	v_pk_fma_f32 v[18:19], v[54:55], v[126:127], v[18:19] op_sel_hi:[1,0,1]
	v_fmac_f32_dpp v118, v22, v126 row_newbcast:14 row_mask:0xf bank_mask:0xf
	s_waitcnt lgkmcnt(0)
; __device__ __forceinline__ void gdn_item(const Params& p, int item, float* sm) {
;     ...
;       for (int t = 0; t < TC; t++) {
;         const float4 k0 = *(const float4*)(bk + t * 128 + sub * 4);
;         const float4 k1 = *(const float4*)(bk + t * 128 + 64 + sub * 4);
;         const float4 q0 = *(const float4*)(bq + t * 128 + sub * 4);
;         const float4 q1 = *(const float4*)(bq + t * 128 + 64 + sub * 4);
;         const float v = bv[t * 16 + cw];
;         const float g = bg[t], be = bg[TC + t];
;         const float qk = bo[TC * 16 + t];
;         float pa = k0.x * S[0] + k0.y * S[1];
;         float pb2 = k0.z * S[2] + k0.w * S[3];
;         float qa = q0.x * S[0] + q0.y * S[1];
;         float qb2 = q0.z * S[2] + q0.w * S[3];
;         pa += k1.x * S[4] + k1.y * S[5];
;         pb2 += k1.z * S[6] + k1.w * S[7];
;         qa += q1.x * S[4] + q1.y * S[5];
;         qb2 += q1.z * S[6] + q1.w * S[7];
;         const float ks = dpp_sum16(pa + pb2);
;         const float qs = dpp_sum16(qa + qb2);
;         const float coef = be * (v - g * ks);
;         const float oo = g * qs + coef * qk;
;         S[0] = g * S[0] + coef * k0.x; S[1] = g * S[1] + coef * k0.y; S[2] = g * S[2] + coef * k0.z; S[3] = g * S[3] + coef * k0.w;
;         S[4] = g * S[4] + coef * k1.x; S[5] = g * S[5] + coef * k1.y; S[6] = g * S[6] + coef * k1.z; S[7] = g * S[7] + coef * k1.w;
;         oreg[t] = oo * 0.08838834764831845f;
;       }
;       if (sub == 0) {
; #pragma unroll
;         for (int t = 0; t < TC; t++) bo[t * 16 + cw] = oreg[t];
	v_pk_mul_f32 v[120:121], v[12:13], v[64:65]
	v_pk_fma_f32 v[120:121], v[14:15], v[66:67], v[120:121]
	v_pk_fma_f32 v[120:121], v[16:17], v[68:69], v[120:121]
	v_pk_fma_f32 v[120:121], v[18:19], v[70:71], v[120:121]
	v_pk_mul_f32 v[122:123], v[12:13], v[72:73]
	v_add_f32_e32 v124, v120, v121
	v_pk_fma_f32 v[122:123], v[14:15], v[74:75], v[122:123]
	v_pk_fma_f32 v[122:123], v[16:17], v[76:77], v[122:123]
	v_add_f32_dpp v124, v124, v124 quad_perm:[1,0,3,2] row_mask:0xf bank_mask:0xf bound_ctrl:1
	v_pk_fma_f32 v[122:123], v[18:19], v[78:79], v[122:123]
	s_nop 0
	v_add_f32_dpp v124, v124, v124 quad_perm:[2,3,0,1] row_mask:0xf bank_mask:0xf bound_ctrl:1
	v_add_f32_e32 v119, v122, v123
	s_nop 0
	v_add_f32_dpp v124, v124, v124 row_half_mirror row_mask:0xf bank_mask:0xf bound_ctrl:1
	s_nop 1
	v_add_f32_dpp v124, v124, v124 row_mirror row_mask:0xf bank_mask:0xf bound_ctrl:1
	v_fmac_f32_dpp v103, v20, v124 row_newbcast:15 row_mask:0xf bank_mask:0xf
	v_mul_f32_dpp v126, v21, v103 row_newbcast:15 row_mask:0xf bank_mask:0xf
	v_pk_fma_f32 v[12:13], v[64:65], v[126:127], v[12:13] op_sel_hi:[1,0,1]
	v_pk_fma_f32 v[14:15], v[66:67], v[126:127], v[14:15] op_sel_hi:[1,0,1]
	v_pk_fma_f32 v[16:17], v[68:69], v[126:127], v[16:17] op_sel_hi:[1,0,1]
	v_pk_fma_f32 v[18:19], v[70:71], v[126:127], v[18:19] op_sel_hi:[1,0,1]
	v_fmac_f32_dpp v119, v22, v126 row_newbcast:15 row_mask:0xf bank_mask:0xf
	v_mov_b32_dpp v126, v20 row_newbcast:15 row_mask:0xf bank_mask:0xf
	v_add_f32_dpp v104, v104, v104 quad_perm:[1,0,3,2] row_mask:0xf bank_mask:0xf bound_ctrl:1
	v_add_f32_dpp v105, v105, v105 quad_perm:[1,0,3,2] row_mask:0xf bank_mask:0xf bound_ctrl:1
	v_add_f32_dpp v106, v106, v106 quad_perm:[1,0,3,2] row_mask:0xf bank_mask:0xf bound_ctrl:1
	v_add_f32_dpp v107, v107, v107 quad_perm:[1,0,3,2] row_mask:0xf bank_mask:0xf bound_ctrl:1
	v_add_f32_dpp v108, v108, v108 quad_perm:[1,0,3,2] row_mask:0xf bank_mask:0xf bound_ctrl:1
	v_add_f32_dpp v109, v109, v109 quad_perm:[1,0,3,2] row_mask:0xf bank_mask:0xf bound_ctrl:1
	v_add_f32_dpp v110, v110, v110 quad_perm:[1,0,3,2] row_mask:0xf bank_mask:0xf bound_ctrl:1
	v_add_f32_dpp v111, v111, v111 quad_perm:[1,0,3,2] row_mask:0xf bank_mask:0xf bound_ctrl:1
	v_add_f32_dpp v112, v112, v112 quad_perm:[1,0,3,2] row_mask:0xf bank_mask:0xf bound_ctrl:1
	v_add_f32_dpp v113, v113, v113 quad_perm:[1,0,3,2] row_mask:0xf bank_mask:0xf bound_ctrl:1
	v_add_f32_dpp v114, v114, v114 quad_perm:[1,0,3,2] row_mask:0xf bank_mask:0xf bound_ctrl:1
	v_add_f32_dpp v115, v115, v115 quad_perm:[1,0,3,2] row_mask:0xf bank_mask:0xf bound_ctrl:1
	v_add_f32_dpp v116, v116, v116 quad_perm:[1,0,3,2] row_mask:0xf bank_mask:0xf bound_ctrl:1
	v_add_f32_dpp v117, v117, v117 quad_perm:[1,0,3,2] row_mask:0xf bank_mask:0xf bound_ctrl:1
	v_add_f32_dpp v118, v118, v118 quad_perm:[1,0,3,2] row_mask:0xf bank_mask:0xf bound_ctrl:1
	v_add_f32_dpp v119, v119, v119 quad_perm:[1,0,3,2] row_mask:0xf bank_mask:0xf bound_ctrl:1
	v_pk_mul_f32 v[12:13], v[12:13], v[126:127] op_sel_hi:[1,0] neg_lo:[0,1] neg_hi:[0,1]
	v_pk_mul_f32 v[14:15], v[14:15], v[126:127] op_sel_hi:[1,0] neg_lo:[0,1] neg_hi:[0,1]
	v_pk_mul_f32 v[16:17], v[16:17], v[126:127] op_sel_hi:[1,0] neg_lo:[0,1] neg_hi:[0,1]
	v_pk_mul_f32 v[18:19], v[18:19], v[126:127] op_sel_hi:[1,0] neg_lo:[0,1] neg_hi:[0,1]
	v_add_f32_dpp v104, v104, v104 quad_perm:[2,3,0,1] row_mask:0xf bank_mask:0xf bound_ctrl:1
	v_add_f32_dpp v105, v105, v105 quad_perm:[2,3,0,1] row_mask:0xf bank_mask:0xf bound_ctrl:1
	v_add_f32_dpp v106, v106, v106 quad_perm:[2,3,0,1] row_mask:0xf bank_mask:0xf bound_ctrl:1
	v_add_f32_dpp v107, v107, v107 quad_perm:[2,3,0,1] row_mask:0xf bank_mask:0xf bound_ctrl:1
	v_add_f32_dpp v108, v108, v108 quad_perm:[2,3,0,1] row_mask:0xf bank_mask:0xf bound_ctrl:1
	v_add_f32_dpp v109, v109, v109 quad_perm:[2,3,0,1] row_mask:0xf bank_mask:0xf bound_ctrl:1
	v_add_f32_dpp v110, v110, v110 quad_perm:[2,3,0,1] row_mask:0xf bank_mask:0xf bound_ctrl:1
	v_add_f32_dpp v111, v111, v111 quad_perm:[2,3,0,1] row_mask:0xf bank_mask:0xf bound_ctrl:1
	v_add_f32_dpp v112, v112, v112 quad_perm:[2,3,0,1] row_mask:0xf bank_mask:0xf bound_ctrl:1
	v_add_f32_dpp v113, v113, v113 quad_perm:[2,3,0,1] row_mask:0xf bank_mask:0xf bound_ctrl:1
	v_add_f32_dpp v114, v114, v114 quad_perm:[2,3,0,1] row_mask:0xf bank_mask:0xf bound_ctrl:1
	v_add_f32_dpp v115, v115, v115 quad_perm:[2,3,0,1] row_mask:0xf bank_mask:0xf bound_ctrl:1
	v_add_f32_dpp v116, v116, v116 quad_perm:[2,3,0,1] row_mask:0xf bank_mask:0xf bound_ctrl:1
	v_add_f32_dpp v117, v117, v117 quad_perm:[2,3,0,1] row_mask:0xf bank_mask:0xf bound_ctrl:1
	v_add_f32_dpp v118, v118, v118 quad_perm:[2,3,0,1] row_mask:0xf bank_mask:0xf bound_ctrl:1
	v_add_f32_dpp v119, v119, v119 quad_perm:[2,3,0,1] row_mask:0xf bank_mask:0xf bound_ctrl:1
	v_add_f32_dpp v104, v104, v104 row_half_mirror row_mask:0xf bank_mask:0xf bound_ctrl:1
	v_add_f32_dpp v105, v105, v105 row_half_mirror row_mask:0xf bank_mask:0xf bound_ctrl:1
	v_add_f32_dpp v106, v106, v106 row_half_mirror row_mask:0xf bank_mask:0xf bound_ctrl:1
	v_add_f32_dpp v107, v107, v107 row_half_mirror row_mask:0xf bank_mask:0xf bound_ctrl:1
	v_add_f32_dpp v108, v108, v108 row_half_mirror row_mask:0xf bank_mask:0xf bound_ctrl:1
	v_add_f32_dpp v109, v109, v109 row_half_mirror row_mask:0xf bank_mask:0xf bound_ctrl:1
	v_add_f32_dpp v110, v110, v110 row_half_mirror row_mask:0xf bank_mask:0xf bound_ctrl:1
	v_add_f32_dpp v111, v111, v111 row_half_mirror row_mask:0xf bank_mask:0xf bound_ctrl:1
	v_add_f32_dpp v112, v112, v112 row_half_mirror row_mask:0xf bank_mask:0xf bound_ctrl:1
	v_add_f32_dpp v113, v113, v113 row_half_mirror row_mask:0xf bank_mask:0xf bound_ctrl:1
; __device__ __forceinline__ void gdn_item(const Params& p, int item, float* sm) {
;     ...
;       if (sub == 0) {
; #pragma unroll
;         for (int t = 0; t < TC; t++) bo[t * 16 + cw] = oreg[t];
;       }
;     }
;     if (ch + 1 < NCH) GDN_STORE(bi ^ 1)
;     __syncthreads();
;     {
;       const float ov = sm[bi * BUF + 2 * TC * 128 + TC * 16 + 2 * TC + ltt * 16 + lseg];
;       O[(rowb + t0 + ltt) * D + 512 + h * 128 + c0 + lseg] = f2bf(ov);
;     }
;   }
	v_add_f32_dpp v114, v114, v114 row_half_mirror row_mask:0xf bank_mask:0xf bound_ctrl:1
	v_add_f32_dpp v115, v115, v115 row_half_mirror row_mask:0xf bank_mask:0xf bound_ctrl:1
	v_add_f32_dpp v116, v116, v116 row_half_mirror row_mask:0xf bank_mask:0xf bound_ctrl:1
	v_add_f32_dpp v117, v117, v117 row_half_mirror row_mask:0xf bank_mask:0xf bound_ctrl:1
	v_add_f32_dpp v118, v118, v118 row_half_mirror row_mask:0xf bank_mask:0xf bound_ctrl:1
	v_add_f32_dpp v119, v119, v119 row_half_mirror row_mask:0xf bank_mask:0xf bound_ctrl:1
	v_add_f32_dpp v104, v104, v104 row_mirror row_mask:0xf bank_mask:0xf bound_ctrl:1
	v_add_f32_dpp v105, v105, v105 row_mirror row_mask:0xf bank_mask:0xf bound_ctrl:1
	v_add_f32_dpp v106, v106, v106 row_mirror row_mask:0xf bank_mask:0xf bound_ctrl:1
	v_add_f32_dpp v107, v107, v107 row_mirror row_mask:0xf bank_mask:0xf bound_ctrl:1
	v_add_f32_dpp v108, v108, v108 row_mirror row_mask:0xf bank_mask:0xf bound_ctrl:1
	v_add_f32_dpp v109, v109, v109 row_mirror row_mask:0xf bank_mask:0xf bound_ctrl:1
	v_add_f32_dpp v110, v110, v110 row_mirror row_mask:0xf bank_mask:0xf bound_ctrl:1
	v_add_f32_dpp v111, v111, v111 row_mirror row_mask:0xf bank_mask:0xf bound_ctrl:1
	v_add_f32_dpp v112, v112, v112 row_mirror row_mask:0xf bank_mask:0xf bound_ctrl:1
	v_add_f32_dpp v113, v113, v113 row_mirror row_mask:0xf bank_mask:0xf bound_ctrl:1
	v_add_f32_dpp v114, v114, v114 row_mirror row_mask:0xf bank_mask:0xf bound_ctrl:1
	v_add_f32_dpp v115, v115, v115 row_mirror row_mask:0xf bank_mask:0xf bound_ctrl:1
	v_add_f32_dpp v116, v116, v116 row_mirror row_mask:0xf bank_mask:0xf bound_ctrl:1
	v_add_f32_dpp v117, v117, v117 row_mirror row_mask:0xf bank_mask:0xf bound_ctrl:1
	v_add_f32_dpp v118, v118, v118 row_mirror row_mask:0xf bank_mask:0xf bound_ctrl:1
	v_add_f32_dpp v119, v119, v119 row_mirror row_mask:0xf bank_mask:0xf bound_ctrl:1
	v_mul_f32_dpp v104, v23, v104 row_newbcast:0 row_mask:0xf bank_mask:0xf
	v_mul_f32_dpp v105, v23, v105 row_newbcast:1 row_mask:0xf bank_mask:0xf
	v_mul_f32_dpp v106, v23, v106 row_newbcast:2 row_mask:0xf bank_mask:0xf
	v_mul_f32_dpp v107, v23, v107 row_newbcast:3 row_mask:0xf bank_mask:0xf
	v_mul_f32_dpp v108, v23, v108 row_newbcast:4 row_mask:0xf bank_mask:0xf
	v_mul_f32_dpp v109, v23, v109 row_newbcast:5 row_mask:0xf bank_mask:0xf
	v_mul_f32_dpp v110, v23, v110 row_newbcast:6 row_mask:0xf bank_mask:0xf
	v_mul_f32_dpp v111, v23, v111 row_newbcast:7 row_mask:0xf bank_mask:0xf
	v_mul_f32_dpp v112, v23, v112 row_newbcast:8 row_mask:0xf bank_mask:0xf
	v_mul_f32_dpp v113, v23, v113 row_newbcast:9 row_mask:0xf bank_mask:0xf
	v_mul_f32_dpp v114, v23, v114 row_newbcast:10 row_mask:0xf bank_mask:0xf
	v_mul_f32_dpp v115, v23, v115 row_newbcast:11 row_mask:0xf bank_mask:0xf
	v_mul_f32_dpp v116, v23, v116 row_newbcast:12 row_mask:0xf bank_mask:0xf
	v_mul_f32_dpp v117, v23, v117 row_newbcast:13 row_mask:0xf bank_mask:0xf
	v_mul_f32_dpp v118, v23, v118 row_newbcast:14 row_mask:0xf bank_mask:0xf
	v_mul_f32_dpp v119, v23, v119 row_newbcast:15 row_mask:0xf bank_mask:0xf
	v_add_u32_e32 v41, s1, v130
	s_xor_b32 s2, s1, 0x4900
	v_add_u32_e32 v39, s2, v128
	v_add_u32_e32 v40, s2, v129
	v_add_u32_e32 v43, s2, v133
	ds_write2_b32 v41, v104, v105 offset0:0 offset1:16
	ds_write2_b32 v41, v106, v107 offset0:32 offset1:48
	ds_write2_b32 v41, v108, v109 offset0:64 offset1:80
	ds_write2_b32 v41, v110, v111 offset0:96 offset1:112
	ds_write2_b32 v41, v112, v113 offset0:128 offset1:144
	ds_write2_b32 v41, v114, v115 offset0:160 offset1:176
	ds_write2_b32 v41, v116, v117 offset0:192 offset1:208
	ds_write2_b32 v41, v118, v119 offset0:224 offset1:240
	s_cmp_eq_u32 s0, 512
	s_cbranch_scc1 .Lgd_noprep
	s_waitcnt vmcnt(0)
	v_lshlrev_b32_e32 v48, 16, v28
	v_and_b32_e32 v49, 0xffff0000, v28
	v_lshlrev_b32_e32 v50, 16, v29
	v_and_b32_e32 v51, 0xffff0000, v29
	v_lshlrev_b32_e32 v52, 16, v30
	v_and_b32_e32 v53, 0xffff0000, v30
	v_lshlrev_b32_e32 v54, 16, v31
	v_and_b32_e32 v55, 0xffff0000, v31
	v_lshlrev_b32_e32 v56, 16, v32
	v_and_b32_e32 v57, 0xffff0000, v32
	v_lshlrev_b32_e32 v58, 16, v33
	v_and_b32_e32 v59, 0xffff0000, v33
	v_lshlrev_b32_e32 v60, 16, v34
	v_and_b32_e32 v61, 0xffff0000, v34
	v_lshlrev_b32_e32 v62, 16, v35
	v_and_b32_e32 v63, 0xffff0000, v35
	v_lshlrev_b32_e32 v64, 16, v36
	v_mov_b32_e32 v65, v37
	ds_write_b128 v39, v[48:51]
	ds_write_b128 v39, v[52:55] offset:16
	v_add_f32_dpp v65, v65, v65 row_shr:1 row_mask:0xf bank_mask:0xf bound_ctrl:1
	ds_write_b128 v39, v[56:59] offset:8192
	ds_write_b128 v39, v[60:63] offset:8208
	v_add_f32_dpp v65, v65, v65 row_shr:2 row_mask:0xf bank_mask:0xf bound_ctrl:1
	v_pk_mul_f32 v[66:67], v[48:49], v[56:57]
	v_pk_fma_f32 v[66:67], v[50:51], v[58:59], v[66:67]
	v_add_f32_dpp v65, v65, v65 row_shr:4 row_mask:0xf bank_mask:0xf bound_ctrl:1
	v_pk_fma_f32 v[66:67], v[52:53], v[60:61], v[66:67]
	v_pk_fma_f32 v[66:67], v[54:55], v[62:63], v[66:67]
	v_add_f32_dpp v65, v65, v65 row_shr:8 row_mask:0xf bank_mask:0xf bound_ctrl:1
	v_add_f32_e32 v68, v66, v67
	ds_write_b32 v40, v64
	v_max_f32_e32 v65, 0xc2a00000, v65
	v_add_f32_dpp v68, v68, v68 quad_perm:[1,0,3,2] row_mask:0xf bank_mask:0xf bound_ctrl:1
	v_mul_f32_e32 v65, 0x3fb8aa3b, v65
	s_nop 0
	v_add_f32_dpp v68, v68, v68 quad_perm:[2,3,0,1] row_mask:0xf bank_mask:0xf bound_ctrl:1
	v_exp_f32_e32 v69, v65
	v_exp_f32_e64 v70, -v65
	v_add_f32_dpp v68, v68, v68 row_half_mirror row_mask:0xf bank_mask:0xf bound_ctrl:1
	s_nop 1
	v_add_f32_dpp v68, v68, v68 row_mirror row_mask:0xf bank_mask:0xf bound_ctrl:1
	v_mul_f32_e32 v23, 0x3db504f3, v69
	v_mul_f32_e32 v21, v38, v70
	v_sub_f32_e32 v20, 0, v69
	ds_write_b32 v43, v68
	s_add_u32 s4, s4, 0xc000
	s_addc_u32 s5, s5, 0
	s_add_u32 s6, s6, 0x200
	s_addc_u32 s7, s7, 0
.Lgd_noprep:
	v_add_u32_e32 v42, s1, v131
	v_add_u32_e32 v10, s2, v45
	v_add_u32_e32 v11, s2, v132
	v_add_u32_e32 v44, s2, v134
	s_waitcnt lgkmcnt(0)
	s_barrier
	ds_read_b32 v120, v42
	ds_read_b32 v22, v44
	ds_read_b128 v[88:91], v11 offset:0
	ds_read_b128 v[92:95], v11 offset:16
	ds_read_b128 v[96:99], v11 offset:32
	ds_read_b128 v[100:103], v11 offset:48
	ds_read_b128 v[48:51], v10 offset:8192
	ds_read_b128 v[52:55], v10 offset:8448
	ds_read_b128 v[56:59], v10
	ds_read_b128 v[60:63], v10 offset:256
	s_waitcnt lgkmcnt(9)
	v_cvt_pk_bf16_f32 v120, v120, v120
	s_waitcnt lgkmcnt(8)
	v_mul_f32_e32 v22, 0x3d800000, v22
	global_store_short v27, v120, s[8:9]
	s_add_u32 s8, s8, 0x8000
	s_addc_u32 s9, s9, 0
	s_mov_b32 s1, s2
	s_add_i32 s0, s0, 1
	s_cmp_lg_u32 s0, 513
	s_cbranch_scc1 .Lgd_chunk
	s_waitcnt lgkmcnt(0)
